# nt hint also on the weight-conversion source loads (f32 weights streamed once in the prep phase)
# speedup vs baseline: 1.0014x; 1.0014x over previous
.Lconv_48:
	s_lshl_b32 s20, s39, 6
	v_add_u32_e32 v105, s20, v38
	v_cmp_gt_i32_e32 vcc, s4, v92
	v_ashrrev_i32_e32 v93, 31, v92
	v_lshl_add_u64 v[126:127], v[92:93], 2, s[8:9]
	v_add_u32_e32 v101, 16, v105
	v_add_u32_e32 v106, 32, v105
	v_add_u32_e32 v125, 48, v105
	v_mov_b32_e32 v76, 0
	v_mov_b32_e32 v77, 0
	v_mov_b32_e32 v78, 0
	v_mov_b32_e32 v79, 0
	v_mov_b32_e32 v80, 0
	v_mov_b32_e32 v81, 0
	v_mov_b32_e32 v82, 0
	v_mov_b32_e32 v83, 0
	v_mov_b32_e32 v84, 0
	v_mov_b32_e32 v85, 0
	v_mov_b32_e32 v86, 0
	v_mov_b32_e32 v87, 0
	v_mov_b32_e32 v88, 0
	v_mov_b32_e32 v89, 0
	v_mov_b32_e32 v90, 0
	v_mov_b32_e32 v91, 0
	v_mad_i64_i32 v[92:93], s[40:41], v105, s4, 0
	v_mad_i64_i32 v[94:95], s[40:41], v101, s4, 0
	v_mad_i64_i32 v[96:97], s[40:41], v106, s4, 0
	v_mad_i64_i32 v[98:99], s[40:41], v125, s4, 0
	v_lshl_add_u64 v[92:93], v[92:93], 2, v[126:127]
	v_lshl_add_u64 v[94:95], v[94:95], 2, v[126:127]
	v_lshl_add_u64 v[96:97], v[96:97], 2, v[126:127]
	v_lshl_add_u64 v[98:99], v[98:99], 2, v[126:127]
	s_mov_b64 s[36:37], exec
	v_cmp_gt_i32_e64 s[0:1], s5, v105
	s_nop 0
	s_and_b64 s[0:1], s[0:1], vcc
	s_and_b64 exec, s[36:37], s[0:1]
	global_load_dwordx4 v[76:79], v[92:93], off nt
	s_mov_b64 exec, s[36:37]
	v_cmp_gt_i32_e64 s[0:1], s5, v101
	s_nop 0
	s_and_b64 s[0:1], s[0:1], vcc
	s_and_b64 exec, s[36:37], s[0:1]
	global_load_dwordx4 v[80:83], v[94:95], off nt
	s_mov_b64 exec, s[36:37]
	v_cmp_gt_i32_e64 s[0:1], s5, v106
	s_nop 0
	s_and_b64 s[0:1], s[0:1], vcc
	s_and_b64 exec, s[36:37], s[0:1]
	global_load_dwordx4 v[84:87], v[96:97], off nt
	s_mov_b64 exec, s[36:37]
	v_cmp_gt_i32_e64 s[0:1], s5, v125
	s_nop 0
	s_and_b64 s[0:1], s[0:1], vcc
	s_and_b64 exec, s[36:37], s[0:1]
	global_load_dwordx4 v[88:91], v[98:99], off nt
	s_mov_b64 exec, s[36:37]
	s_mov_b64 s[0:1], 0
	v_mov_b32_e32 v105, v14

.LBB0_48:
	s_lshl_b32 s20, s39, 6
	v_add_u32_e32 v105, s20, v38
	v_cmp_gt_i32_e32 vcc, s4, v92
	v_ashrrev_i32_e32 v93, 31, v92
	v_lshl_add_u64 v[126:127], v[92:93], 2, s[8:9]
	v_add_u32_e32 v101, 16, v105
	v_add_u32_e32 v106, 32, v105
	v_add_u32_e32 v125, 48, v105
	v_mov_b32_e32 v76, 0
	v_mov_b32_e32 v77, 0
	v_mov_b32_e32 v78, 0
	v_mov_b32_e32 v79, 0
	v_mov_b32_e32 v80, 0
	v_mov_b32_e32 v81, 0
	v_mov_b32_e32 v82, 0
	v_mov_b32_e32 v83, 0
	v_mov_b32_e32 v84, 0
	v_mov_b32_e32 v85, 0
	v_mov_b32_e32 v86, 0
	v_mov_b32_e32 v87, 0
	v_mov_b32_e32 v88, 0
	v_mov_b32_e32 v89, 0
	v_mov_b32_e32 v90, 0
	v_mov_b32_e32 v91, 0
	v_mad_i64_i32 v[92:93], s[40:41], v105, s4, 0
	v_mad_i64_i32 v[94:95], s[40:41], v101, s4, 0
	v_mad_i64_i32 v[96:97], s[40:41], v106, s4, 0
	v_mad_i64_i32 v[98:99], s[40:41], v125, s4, 0
	v_lshl_add_u64 v[92:93], v[92:93], 2, v[126:127]
	v_lshl_add_u64 v[94:95], v[94:95], 2, v[126:127]
	v_lshl_add_u64 v[96:97], v[96:97], 2, v[126:127]
	v_lshl_add_u64 v[98:99], v[98:99], 2, v[126:127]
	s_mov_b64 s[36:37], exec
	v_cmp_gt_i32_e64 s[0:1], s5, v105
	s_nop 0
	s_and_b64 s[0:1], s[0:1], vcc
	s_and_b64 exec, s[36:37], s[0:1]
	global_load_dwordx4 v[76:79], v[92:93], off nt
	s_mov_b64 exec, s[36:37]
	v_cmp_gt_i32_e64 s[0:1], s5, v101
	s_nop 0
	s_and_b64 s[0:1], s[0:1], vcc
	s_and_b64 exec, s[36:37], s[0:1]
	global_load_dwordx4 v[80:83], v[94:95], off nt
	s_mov_b64 exec, s[36:37]
	v_cmp_gt_i32_e64 s[0:1], s5, v106
	s_nop 0
	s_and_b64 s[0:1], s[0:1], vcc
	s_and_b64 exec, s[36:37], s[0:1]
	global_load_dwordx4 v[84:87], v[96:97], off nt
	s_mov_b64 exec, s[36:37]
	v_cmp_gt_i32_e64 s[0:1], s5, v125
	s_nop 0
	s_and_b64 s[0:1], s[0:1], vcc
	s_and_b64 exec, s[36:37], s[0:1]
	global_load_dwordx4 v[88:91], v[98:99], off nt
	s_mov_b64 exec, s[36:37]
	s_mov_b64 s[0:1], 0
	v_mov_b32_e32 v105, v14
	s_waitcnt vmcnt(0)
	s_branch .Lconv_b1
